# P6: only the last quarter of the epilogue (2 row-blocks) deferred into the next unit's first K-iteration
# baseline (speedup 1.0000x reference)
; #define PG8_STAGE(bufoff, gbase, voff) do { _Pragma("unroll") for (int _i = 0; _i < 2; ++_i) \
;         __builtin_amdgcn_global_load_lds((const unsigned*)((const char*)(gbase) + (voff)[_i]), (PG8_LAS unsigned*)(lds + (bufoff) + ldsw + _i * 8192), 16, 0, 0); } while (0)
; #define PG8_LDA(dst, b, h) do { _Pragma("unroll") for (int m = 0; m < 4; ++m) _Pragma("unroll") for (int k = 0; k < 2; ++k) dst[m][k] = *(const PG8_LAS bf16x8*)(lds + PG8_SA(b, h) + aoff + m * 2048 + k * 1024); } while (0)
; #define PG8_LDB(dst, b, h) do { _Pragma("unroll") for (int n = 0; n < 2; ++n) _Pragma("unroll") for (int k = 0; k < 2; ++k) dst[n][k] = *(const PG8_LAS bf16x8*)(lds + PG8_SB(b, h) + boff + n * 2048 + k * 1024); } while (0)
; #define PG8_MMA(ai, bj, At, Bt) do { __builtin_amdgcn_s_setprio(1); _Pragma("unroll") for (int m = 0; m < 4; ++m) _Pragma("unroll") for (int n = 0; n < 2; ++n) _Pragma("unroll") for (int k = 0; k < 2; ++k) \
;         acc[ai][bj][m][n] = __builtin_amdgcn_mfma_f32_16x16x32_bf16(Bt[n][k], At[m][k], acc[ai][bj][m][n], 0, 0, 0); __builtin_amdgcn_s_setprio(0); } while (0)
; template <class Epi, class Sched, bool ALIGN_EPI = false, bool SP2 = false>
; __device__ __forceinline__ void gemm_phase(PG8_LAS unsigned char* lds, const Gemm g, const Sched& S, const Epi& E) {
;     ...
;             PG8_LDB(B0, 0, 0); PG8_LDB(B1, 0, 1); PG8_SCHED; PG8_LDA(At, 0, 0); PG8_STAGE(PG8_SA(1, 1), a1 + hstep, voffA);
;             PG8_WAIT_V(8); PG8_WAIT_L(0); PG8_BAR; PG8_MMA(0, 0, At, B0); PG8_MMA(0, 1, At, B1); PG8_BAR; PG8_SCHED;
;     __device__ __forceinline__ void operator()(const f32x4 (&acc)[2][2][4][2], const pg8::Unit& u, int wr, int wc, int fr, int fq) const {
;     ...
;         for (int ai = 0; ai < 2; ++ai)
; #pragma unroll
;             for (int m = 0; m < 4; ++m) {
;                 const int row = row0 + ai * 128 + m * 16;
;                 const float rs = sumsq ? rsqrtf(sumsq[row] * (1.f / 1024.f) + EPS) : 1.f;
;                 float o[8];
; #pragma unroll
;                 for (int n = 0; n < 2; ++n)
; #pragma unroll
;                     for (int e = 0; e < 4; ++e) { const float g = acc[ai][0][m][n][e] * rs, up = acc[ai][1][m][n][e] * rs; o[4 * n + e] = silu_f(g) * up; }
;                 u32x4 w; w.x = pk2(o[0], o[1]); w.y = pk2(o[2], o[3]); w.z = pk2(o[4], o[5]); w.w = pk2(o[6], o[7]);
;                 *(u32x4*)(H + (size_t)row * DFF + col) = w;
.LBB0_781:
	s_ashr_i32 s17, s16, 31
	s_lshl_b64 s[18:19], s[16:17], 19
	s_add_u32 s18, s8, s18
	s_addc_u32 s19, s9, s19
	s_and_b64 s[20:21], s[4:5], exec
	s_cselect_b32 s17, s19, s23
	s_cselect_b32 s47, s18, s22
	s_ashr_i32 s15, s14, 31
	s_lshl_b64 s[20:21], s[14:15], 19
	s_add_u32 s20, s28, s20
	s_addc_u32 s21, s29, s21
	s_and_b64 s[26:27], s[4:5], exec
	s_cselect_b32 s15, s21, s25
	s_cselect_b32 s48, s20, s24
	s_add_u32 s22, s22, 0x40080
	s_addc_u32 s23, s23, 0
	s_add_u32 s49, s24, 0x100
	s_addc_u32 s50, s25, 0
	s_mov_b32 s51, -2
	s_cmp_eq_u32 s98, 0
	s_cbranch_scc1 .Lp6_plain
	ds_read_b128 v[144:147], v151
	ds_read_b128 v[156:159], v151 offset:1024
	ds_read_b128 v[160:163], v151 offset:2048
	ds_read_b128 v[164:167], v151 offset:3072
	ds_read_b128 v[168:171], v152
	ds_read_b128 v[172:175], v152 offset:1024
	ds_read_b128 v[176:179], v152 offset:2048
	ds_read_b128 v[180:183], v152 offset:3072
	s_add_u32 s24, s22, 0xfffc0080
	s_addc_u32 s25, s23, -1
	s_cmp_eq_u32 s51, 12
	s_cselect_b32 s27, s17, s25
	s_cselect_b32 s26, s47, s24
	s_cselect_b32 s25, s15, s50
	s_cselect_b32 s24, s48, s49
	v_lshl_add_u64 v[218:219], s[22:23], 0, v[136:137]
	s_add_i32 m0, s34, 0xc000
	ds_read_b128 v[184:187], v153
	ds_read_b128 v[190:193], v153 offset:1024
	ds_read_b128 v[194:197], v153 offset:2048
	ds_read_b128 v[198:201], v153 offset:3072
	ds_read_b128 v[202:205], v153 offset:4096
	ds_read_b128 v[206:209], v153 offset:5120
	ds_read_b128 v[210:213], v153 offset:6144
	ds_read_b128 v[214:217], v153 offset:7168
	global_load_lds_dwordx4 v[218:219], off
	v_lshl_add_u64 v[218:219], s[22:23], 0, v[138:139]
	s_add_i32 m0, s34, 0xe000
	s_nop 0
	global_load_lds_dwordx4 v[218:219], off
	s_nop 0
	s_nop 0
	v_mov_b32_e32 v33, v24
	v_mov_b32_e32 v24, v29
	v_mov_b32_e32 v29, v26
	v_mov_b32_e32 v26, v31
	v_mov_b32_e32 v31, v16
	v_mov_b32_e32 v16, v21
	v_mov_b32_e32 v21, v18
	v_mov_b32_e32 v18, v23
	v_mov_b32_e32 v32, v28
	v_mov_b32_e32 v28, v30
	v_mov_b32_e32 v30, v20
	v_mov_b32_e32 v20, v22
	v_add_u32_e32 v22, 0xa0, v228
	s_nop 0
	v_fmamk_f32 v23, v241, 0x3a800000, v154
	v_mul_f32_e32 v34, 0x4b800000, v23
	v_cmp_gt_f32_e32 vcc, s45, v23
	s_nop 1
	v_cndmask_b32_e32 v23, v23, v34, vcc
	v_rsq_f32_e32 v34, v23
	v_mad_i64_i32 v[22:23], s[100:101], v22, s46, v[120:121]
	v_lshl_add_u64 v[22:23], v[22:23], 0, v[122:123]
	v_mul_f32_e32 v35, 0x45800000, v34
	v_cndmask_b32_e32 v34, v34, v35, vcc
	v_pk_mul_f32 v[18:19], v[18:19], v[34:35] op_sel_hi:[1,0]
	v_pk_mul_f32 v[32:33], v[32:33], v[34:35] op_sel_hi:[1,0]
	v_pk_mul_f32 v[24:25], v[24:25], v[34:35] op_sel_hi:[1,0]
	v_pk_mul_f32 v[28:29], v[28:29], v[34:35] op_sel_hi:[1,0]
	v_pk_mul_f32 v[26:27], v[26:27], v[34:35] op_sel_hi:[1,0]
	v_pk_mul_f32 v[30:31], v[30:31], v[34:35] op_sel_hi:[1,0]
	v_pk_mul_f32 v[16:17], v[16:17], v[34:35] op_sel_hi:[1,0]
	v_pk_mul_f32 v[20:21], v[20:21], v[34:35] op_sel_hi:[1,0]
	v_mul_f32_e32 v41, 0xbfb8aa3b, v19
	v_mul_f32_e32 v34, 0xbfb8aa3b, v33
	v_mul_f32_e32 v35, 0xbfb8aa3b, v25
	v_mul_f32_e32 v36, 0xbfb8aa3b, v29
	v_mul_f32_e32 v37, 0xbfb8aa3b, v27
	v_mul_f32_e32 v38, 0xbfb8aa3b, v31
	v_mul_f32_e32 v39, 0xbfb8aa3b, v17
	v_mul_f32_e32 v40, 0xbfb8aa3b, v21
	v_exp_f32_e32 v41, v41
	v_exp_f32_e32 v34, v34
	v_exp_f32_e32 v35, v35
	v_exp_f32_e32 v36, v36
	v_exp_f32_e32 v37, v37
	v_exp_f32_e32 v38, v38
	v_exp_f32_e32 v39, v39
	v_exp_f32_e32 v40, v40
	v_add_f32_e32 v41, 1.0, v41
	v_add_f32_e32 v34, 1.0, v34
	v_add_f32_e32 v35, 1.0, v35
	v_add_f32_e32 v36, 1.0, v36
	v_add_f32_e32 v37, 1.0, v37
	v_add_f32_e32 v38, 1.0, v38
	v_add_f32_e32 v39, 1.0, v39
	v_add_f32_e32 v40, 1.0, v40
	v_rcp_f32_e32 v41, v41
	v_rcp_f32_e32 v34, v34
	v_rcp_f32_e32 v35, v35
	v_rcp_f32_e32 v36, v36
	v_rcp_f32_e32 v37, v37
	v_rcp_f32_e32 v38, v38
	v_rcp_f32_e32 v39, v39
	v_rcp_f32_e32 v40, v40
	v_mul_f32_e32 v19, v19, v41
	v_mul_f32_e32 v33, v33, v34
	v_mul_f32_e32 v25, v25, v35
	v_mul_f32_e32 v29, v29, v36
	v_mul_f32_e32 v27, v27, v37
	v_mul_f32_e32 v31, v31, v38
	v_mul_f32_e32 v17, v17, v39
	v_mul_f32_e32 v21, v21, v40
	v_mul_f32_e32 v19, v18, v19
	v_mul_f32_e32 v32, v32, v33
	v_mul_f32_e32 v24, v24, v25
	v_mul_f32_e32 v25, v28, v29
	v_mul_f32_e32 v26, v26, v27
	v_mul_f32_e32 v27, v30, v31
	v_mul_f32_e32 v28, v16, v17
	v_mul_f32_e32 v20, v20, v21
	v_cvt_pk_bf16_f32 v16, v32, v24
	v_cvt_pk_bf16_f32 v17, v25, v26
	v_cvt_pk_bf16_f32 v18, v27, v28
	v_cvt_pk_bf16_f32 v19, v20, v19
	global_store_dwordx4 v[22:23], v[16:19], off
	s_nop 0
	v_mov_b32_e32 v17, v8
	v_mov_b32_e32 v8, v13
	v_mov_b32_e32 v13, v10
	v_mov_b32_e32 v10, v15
	v_mov_b32_e32 v15, v0
	v_mov_b32_e32 v0, v5
	v_mov_b32_e32 v5, v2
	v_mov_b32_e32 v2, v7
	v_mov_b32_e32 v16, v12
	v_mov_b32_e32 v12, v14
	v_mov_b32_e32 v14, v4
	v_mov_b32_e32 v4, v6
	v_add_u32_e32 v6, 0xb0, v228
	s_nop 0
	v_fmamk_f32 v7, v242, 0x3a800000, v154
	v_mul_f32_e32 v18, 0x4b800000, v7
	v_cmp_gt_f32_e64 vcc, s45, v7
	s_nop 1
	v_cndmask_b32_e64 v7, v7, v18, vcc
	v_rsq_f32_e32 v18, v7
	v_mad_i64_i32 v[6:7], s[100:101], v6, s46, v[120:121]
	v_lshl_add_u64 v[6:7], v[6:7], 0, v[122:123]
	v_mul_f32_e32 v19, 0x45800000, v18
	v_cndmask_b32_e64 v18, v18, v19, vcc
	v_pk_mul_f32 v[2:3], v[2:3], v[18:19] op_sel_hi:[1,0]
	v_pk_mul_f32 v[16:17], v[16:17], v[18:19] op_sel_hi:[1,0]
	v_pk_mul_f32 v[8:9], v[8:9], v[18:19] op_sel_hi:[1,0]
	v_pk_mul_f32 v[12:13], v[12:13], v[18:19] op_sel_hi:[1,0]
	v_pk_mul_f32 v[10:11], v[10:11], v[18:19] op_sel_hi:[1,0]
	v_pk_mul_f32 v[14:15], v[14:15], v[18:19] op_sel_hi:[1,0]
	v_pk_mul_f32 v[0:1], v[0:1], v[18:19] op_sel_hi:[1,0]
	v_pk_mul_f32 v[4:5], v[4:5], v[18:19] op_sel_hi:[1,0]
	v_mul_f32_e32 v25, 0xbfb8aa3b, v3
	v_mul_f32_e32 v18, 0xbfb8aa3b, v17
	v_mul_f32_e32 v19, 0xbfb8aa3b, v9
; #define PG8_STAGE(bufoff, gbase, voff) do { _Pragma("unroll") for (int _i = 0; _i < 2; ++_i) \
;         __builtin_amdgcn_global_load_lds((const unsigned*)((const char*)(gbase) + (voff)[_i]), (PG8_LAS unsigned*)(lds + (bufoff) + ldsw + _i * 8192), 16, 0, 0); } while (0)
; #define PG8_LDA(dst, b, h) do { _Pragma("unroll") for (int m = 0; m < 4; ++m) _Pragma("unroll") for (int k = 0; k < 2; ++k) dst[m][k] = *(const PG8_LAS bf16x8*)(lds + PG8_SA(b, h) + aoff + m * 2048 + k * 1024); } while (0)
; #define PG8_MMA(ai, bj, At, Bt) do { __builtin_amdgcn_s_setprio(1); _Pragma("unroll") for (int m = 0; m < 4; ++m) _Pragma("unroll") for (int n = 0; n < 2; ++n) _Pragma("unroll") for (int k = 0; k < 2; ++k) \
;         acc[ai][bj][m][n] = __builtin_amdgcn_mfma_f32_16x16x32_bf16(Bt[n][k], At[m][k], acc[ai][bj][m][n], 0, 0, 0); __builtin_amdgcn_s_setprio(0); } while (0)
; #define PG8_WAIT_V(n) asm volatile("s_waitcnt vmcnt(" #n ")" ::: "memory")
; #define PG8_WAIT_L(n) asm volatile("s_waitcnt lgkmcnt(" #n ")" ::: "memory")
; #define PG8_BAR __builtin_amdgcn_s_barrier()
; #define PG8_SCHED __builtin_amdgcn_sched_barrier(0)
; __device__ __forceinline__ unsigned pk2(float lo, float hi) { return pg8::cvt_pk_bf16(lo, hi); }
; __device__ __forceinline__ float silu_f(float x) { return x * sigmoid_f(x); }
; template <class Epi, class Sched, bool ALIGN_EPI = false, bool SP2 = false>
; __device__ __forceinline__ void gemm_phase(PG8_LAS unsigned char* lds, const Gemm g, const Sched& S, const Epi& E) {
;     ...
;             PG8_WAIT_V(8); PG8_WAIT_L(0); PG8_BAR; PG8_MMA(0, 0, At, B0); PG8_MMA(0, 1, At, B1); PG8_BAR; PG8_SCHED;
;             PG8_LDA(At, 0, 1); PG8_STAGE(PG8_SB(0, 0), b2, voffB); PG8_STAGE(PG8_SB(0, 1), b2 + hstep, voffB); PG8_STAGE(PG8_SA(0, 0), a2, voffA);
;             PG8_WAIT_V(8); PG8_WAIT_L(0); PG8_BAR; PG8_MMA(1, 0, At, B0); PG8_MMA(1, 1, At, B1); PG8_BAR; PG8_SCHED;
;     __device__ __forceinline__ void operator()(const f32x4 (&acc)[2][2][4][2], const pg8::Unit& u, int wr, int wc, int fr, int fq) const {
;     ...
;                     for (int e = 0; e < 4; ++e) { const float g = acc[ai][0][m][n][e] * rs, up = acc[ai][1][m][n][e] * rs; o[4 * n + e] = silu_f(g) * up; }
;                 u32x4 w; w.x = pk2(o[0], o[1]); w.y = pk2(o[2], o[3]); w.z = pk2(o[4], o[5]); w.w = pk2(o[6], o[7]);
;                 *(u32x4*)(H + (size_t)row * DFF + col) = w;
	v_mul_f32_e32 v20, 0xbfb8aa3b, v13
	v_mul_f32_e32 v21, 0xbfb8aa3b, v11
	v_mul_f32_e32 v22, 0xbfb8aa3b, v15
	v_mul_f32_e32 v23, 0xbfb8aa3b, v1
	v_mul_f32_e32 v24, 0xbfb8aa3b, v5
	v_exp_f32_e32 v25, v25
	v_exp_f32_e32 v18, v18
	v_exp_f32_e32 v19, v19
	v_exp_f32_e32 v20, v20
	v_exp_f32_e32 v21, v21
	v_exp_f32_e32 v22, v22
	v_exp_f32_e32 v23, v23
	v_exp_f32_e32 v24, v24
	v_add_f32_e32 v25, 1.0, v25
	v_add_f32_e32 v18, 1.0, v18
	v_add_f32_e32 v19, 1.0, v19
	v_add_f32_e32 v20, 1.0, v20
	v_add_f32_e32 v21, 1.0, v21
	v_add_f32_e32 v22, 1.0, v22
	v_add_f32_e32 v23, 1.0, v23
	v_add_f32_e32 v24, 1.0, v24
	v_rcp_f32_e32 v25, v25
	v_rcp_f32_e32 v18, v18
	v_rcp_f32_e32 v19, v19
	v_rcp_f32_e32 v20, v20
	v_rcp_f32_e32 v21, v21
	v_rcp_f32_e32 v22, v22
	v_rcp_f32_e32 v23, v23
	v_rcp_f32_e32 v24, v24
	v_mul_f32_e32 v3, v3, v25
	v_mul_f32_e32 v17, v17, v18
	v_mul_f32_e32 v9, v9, v19
	v_mul_f32_e32 v13, v13, v20
	v_mul_f32_e32 v11, v11, v21
	v_mul_f32_e32 v15, v15, v22
	v_mul_f32_e32 v1, v1, v23
	v_mul_f32_e32 v5, v5, v24
	v_mul_f32_e32 v3, v2, v3
	v_mul_f32_e32 v16, v16, v17
	v_mul_f32_e32 v8, v8, v9
	v_mul_f32_e32 v9, v12, v13
	v_mul_f32_e32 v10, v10, v11
	v_mul_f32_e32 v11, v14, v15
	v_mul_f32_e32 v12, v0, v1
	v_mul_f32_e32 v4, v4, v5
	v_cvt_pk_bf16_f32 v0, v16, v8
	v_cvt_pk_bf16_f32 v1, v9, v10
	v_cvt_pk_bf16_f32 v2, v11, v12
	v_cvt_pk_bf16_f32 v3, v4, v3
	global_store_dwordx4 v[6:7], v[0:3], off
	s_waitcnt vmcnt(16)
	s_waitcnt lgkmcnt(0)
	s_barrier
	s_setprio 1
	v_mfma_f32_16x16x32_bf16 v[116:119], v[144:147], v[184:187], 0
	v_mfma_f32_16x16x32_bf16 v[112:115], v[160:163], v[184:187], 0
	v_mfma_f32_16x16x32_bf16 v[100:103], v[144:147], v[194:197], 0
	v_mfma_f32_16x16x32_bf16 v[96:99], v[160:163], v[194:197], 0
	v_mfma_f32_16x16x32_bf16 v[84:87], v[144:147], v[202:205], 0
	v_mfma_f32_16x16x32_bf16 v[80:83], v[160:163], v[202:205], 0
	v_mfma_f32_16x16x32_bf16 v[72:75], v[144:147], v[210:213], 0
	v_mfma_f32_16x16x32_bf16 v[64:67], v[160:163], v[210:213], 0
	v_mfma_f32_16x16x32_bf16 v[116:119], v[156:159], v[190:193], v[116:119]
	v_mfma_f32_16x16x32_bf16 v[112:115], v[164:167], v[190:193], v[112:115]
	v_mfma_f32_16x16x32_bf16 v[100:103], v[156:159], v[198:201], v[100:103]
	v_mfma_f32_16x16x32_bf16 v[96:99], v[164:167], v[198:201], v[96:99]
	v_mfma_f32_16x16x32_bf16 v[84:87], v[156:159], v[206:209], v[84:87]
	v_mfma_f32_16x16x32_bf16 v[80:83], v[164:167], v[206:209], v[80:83]
	v_mfma_f32_16x16x32_bf16 v[72:75], v[156:159], v[214:217], v[72:75]
	v_mfma_f32_16x16x32_bf16 v[64:67], v[164:167], v[214:217], v[64:67]
	v_mfma_f32_16x16x32_bf16 v[124:127], v[168:171], v[184:187], 0
	v_mfma_f32_16x16x32_bf16 v[120:123], v[176:179], v[184:187], 0
	v_mfma_f32_16x16x32_bf16 v[108:111], v[168:171], v[194:197], 0
	v_mfma_f32_16x16x32_bf16 v[104:107], v[176:179], v[194:197], 0
	v_mfma_f32_16x16x32_bf16 v[92:95], v[168:171], v[202:205], 0
	v_mfma_f32_16x16x32_bf16 v[88:91], v[176:179], v[202:205], 0
	v_mfma_f32_16x16x32_bf16 v[76:79], v[168:171], v[210:213], 0
	v_mfma_f32_16x16x32_bf16 v[68:71], v[176:179], v[210:213], 0
	v_mfma_f32_16x16x32_bf16 v[124:127], v[172:175], v[190:193], v[124:127]
	v_mfma_f32_16x16x32_bf16 v[120:123], v[180:183], v[190:193], v[120:123]
	v_mfma_f32_16x16x32_bf16 v[108:111], v[172:175], v[198:201], v[108:111]
	v_mfma_f32_16x16x32_bf16 v[104:107], v[180:183], v[198:201], v[104:107]
	v_mfma_f32_16x16x32_bf16 v[92:95], v[172:175], v[206:209], v[92:95]
	v_mfma_f32_16x16x32_bf16 v[88:91], v[180:183], v[206:209], v[88:91]
	v_mfma_f32_16x16x32_bf16 v[76:79], v[172:175], v[214:217], v[76:79]
	v_mfma_f32_16x16x32_bf16 v[68:71], v[180:183], v[214:217], v[68:71]
	s_setprio 0
	s_barrier
	s_add_i32 s52, s43, s30
	v_lshl_add_u64 v[218:219], s[24:25], 0, v[132:133]
	s_mov_b32 m0, s52
	ds_read_b128 v[184:187], v153 offset:16384
	ds_read_b128 v[190:193], v153 offset:17408
	ds_read_b128 v[194:197], v153 offset:18432
	ds_read_b128 v[198:201], v153 offset:19456
	ds_read_b128 v[202:205], v153 offset:20480
	ds_read_b128 v[206:209], v153 offset:21504
	ds_read_b128 v[210:213], v153 offset:22528
	ds_read_b128 v[214:217], v153 offset:23552
	global_load_lds_dwordx4 v[218:219], off
	s_add_i32 m0, s52, 0x2000
	s_add_u32 s52, s24, 0x40000
	v_lshl_add_u64 v[220:221], s[24:25], 0, v[128:129]
	s_addc_u32 s53, s25, 0
	s_add_i32 s54, s44, s30
	global_load_lds_dwordx4 v[220:221], off
	v_lshl_add_u64 v[222:223], s[52:53], 0, v[132:133]
	s_mov_b32 m0, s54
	v_lshl_add_u64 v[224:225], s[26:27], 0, v[130:131]
	global_load_lds_dwordx4 v[222:223], off
	v_lshl_add_u64 v[222:223], s[52:53], 0, v[128:129]
	s_add_i32 m0, s54, 0x2000
	s_nop 0
	global_load_lds_dwordx4 v[222:223], off
	v_lshl_add_u64 v[222:223], s[26:27], 0, v[134:135]
	s_mov_b32 m0, s34
	s_nop 0
	global_load_lds_dwordx4 v[222:223], off
	s_mov_b32 m0, s35
	s_nop 0
	global_load_lds_dwordx4 v[224:225], off
	s_waitcnt vmcnt(16)
	s_waitcnt lgkmcnt(0)
	s_barrier
; #define PG8_STAGE(bufoff, gbase, voff) do { _Pragma("unroll") for (int _i = 0; _i < 2; ++_i) \
;         __builtin_amdgcn_global_load_lds((const unsigned*)((const char*)(gbase) + (voff)[_i]), (PG8_LAS unsigned*)(lds + (bufoff) + ldsw + _i * 8192), 16, 0, 0); } while (0)
; #define PG8_LDA(dst, b, h) do { _Pragma("unroll") for (int m = 0; m < 4; ++m) _Pragma("unroll") for (int k = 0; k < 2; ++k) dst[m][k] = *(const PG8_LAS bf16x8*)(lds + PG8_SA(b, h) + aoff + m * 2048 + k * 1024); } while (0)
; #define PG8_LDB(dst, b, h) do { _Pragma("unroll") for (int n = 0; n < 2; ++n) _Pragma("unroll") for (int k = 0; k < 2; ++k) dst[n][k] = *(const PG8_LAS bf16x8*)(lds + PG8_SB(b, h) + boff + n * 2048 + k * 1024); } while (0)
; #define PG8_MMA(ai, bj, At, Bt) do { __builtin_amdgcn_s_setprio(1); _Pragma("unroll") for (int m = 0; m < 4; ++m) _Pragma("unroll") for (int n = 0; n < 2; ++n) _Pragma("unroll") for (int k = 0; k < 2; ++k) \
;         acc[ai][bj][m][n] = __builtin_amdgcn_mfma_f32_16x16x32_bf16(Bt[n][k], At[m][k], acc[ai][bj][m][n], 0, 0, 0); __builtin_amdgcn_s_setprio(0); } while (0)
; #define PG8_WAIT_V(n) asm volatile("s_waitcnt vmcnt(" #n ")" ::: "memory")
; #define PG8_WAIT_L(n) asm volatile("s_waitcnt lgkmcnt(" #n ")" ::: "memory")
; #define PG8_BAR __builtin_amdgcn_s_barrier()
; #define PG8_SCHED __builtin_amdgcn_sched_barrier(0)
; template <class Epi, class Sched, bool ALIGN_EPI = false, bool SP2 = false>
; __device__ __forceinline__ void gemm_phase(PG8_LAS unsigned char* lds, const Gemm g, const Sched& S, const Epi& E) {
;     ...
;             PG8_WAIT_V(8); PG8_WAIT_L(0); PG8_BAR; PG8_MMA(1, 0, At, B0); PG8_MMA(1, 1, At, B1); PG8_BAR; PG8_SCHED;
;             PG8_LDB(B0, 1, 0); PG8_LDB(B1, 1, 1); PG8_SCHED; PG8_LDA(At, 1, 0); PG8_STAGE(PG8_SA(0, 1), a2 + hstep, voffA);
;             PG8_WAIT_V(8); PG8_WAIT_L(0); PG8_BAR; PG8_MMA(0, 0, At, B0); PG8_MMA(0, 1, At, B1); PG8_BAR; PG8_SCHED;
	s_setprio 1
	v_mfma_f32_16x16x32_bf16 v[56:59], v[144:147], v[184:187], 0
	v_mfma_f32_16x16x32_bf16 v[48:51], v[160:163], v[184:187], 0
	v_mfma_f32_16x16x32_bf16 v[40:43], v[144:147], v[194:197], 0
	v_mfma_f32_16x16x32_bf16 v[32:35], v[160:163], v[194:197], 0
	v_mfma_f32_16x16x32_bf16 v[24:27], v[144:147], v[202:205], 0
	v_mfma_f32_16x16x32_bf16 v[16:19], v[160:163], v[202:205], 0
	v_mfma_f32_16x16x32_bf16 v[8:11], v[144:147], v[210:213], 0
	v_mfma_f32_16x16x32_bf16 v[0:3], v[160:163], v[210:213], 0
	v_mfma_f32_16x16x32_bf16 v[56:59], v[156:159], v[190:193], v[56:59]
	v_mfma_f32_16x16x32_bf16 v[48:51], v[164:167], v[190:193], v[48:51]
	v_mfma_f32_16x16x32_bf16 v[40:43], v[156:159], v[198:201], v[40:43]
	v_mfma_f32_16x16x32_bf16 v[32:35], v[164:167], v[198:201], v[32:35]
	v_mfma_f32_16x16x32_bf16 v[24:27], v[156:159], v[206:209], v[24:27]
	v_mfma_f32_16x16x32_bf16 v[16:19], v[164:167], v[206:209], v[16:19]
	v_mfma_f32_16x16x32_bf16 v[8:11], v[156:159], v[214:217], v[8:11]
	v_mfma_f32_16x16x32_bf16 v[0:3], v[164:167], v[214:217], v[0:3]
	v_mfma_f32_16x16x32_bf16 v[60:63], v[168:171], v[184:187], 0
	v_mfma_f32_16x16x32_bf16 v[52:55], v[176:179], v[184:187], 0
	v_mfma_f32_16x16x32_bf16 v[44:47], v[168:171], v[194:197], 0
	v_mfma_f32_16x16x32_bf16 v[36:39], v[176:179], v[194:197], 0
	v_mfma_f32_16x16x32_bf16 v[28:31], v[168:171], v[202:205], 0
	v_mfma_f32_16x16x32_bf16 v[20:23], v[176:179], v[202:205], 0
	v_mfma_f32_16x16x32_bf16 v[12:15], v[168:171], v[210:213], 0
	v_mfma_f32_16x16x32_bf16 v[4:7], v[176:179], v[210:213], 0
	v_mfma_f32_16x16x32_bf16 v[60:63], v[172:175], v[190:193], v[60:63]
	v_mfma_f32_16x16x32_bf16 v[52:55], v[180:183], v[190:193], v[52:55]
	v_mfma_f32_16x16x32_bf16 v[44:47], v[172:175], v[198:201], v[44:47]
	v_mfma_f32_16x16x32_bf16 v[36:39], v[180:183], v[198:201], v[36:39]
	v_mfma_f32_16x16x32_bf16 v[28:31], v[172:175], v[206:209], v[28:31]
	v_mfma_f32_16x16x32_bf16 v[20:23], v[180:183], v[206:209], v[20:23]
	v_mfma_f32_16x16x32_bf16 v[12:15], v[172:175], v[214:217], v[12:15]
	v_mfma_f32_16x16x32_bf16 v[4:7], v[180:183], v[214:217], v[4:7]
	s_setprio 0
	s_barrier
	s_add_i32 s52, 0, 0x18000
	v_add_u32_e32 v155, s52, v149
	s_add_i32 s53, 0, 0x1c000
	ds_read_b128 v[144:147], v155
	ds_read_b128 v[156:159], v155 offset:1024
	ds_read_b128 v[160:163], v155 offset:2048
	ds_read_b128 v[164:167], v155 offset:3072
	v_add_u32_e32 v155, s53, v149
	ds_read_b128 v[168:171], v155
	ds_read_b128 v[172:175], v155 offset:1024
	ds_read_b128 v[176:179], v155 offset:2048
	ds_read_b128 v[180:183], v155 offset:3072
	s_add_u32 s26, s26, 0x40000
	s_addc_u32 s27, s27, 0
	s_mov_b32 m0, s36
	v_lshl_add_u64 v[226:227], s[26:27], 0, v[134:135]
	ds_read_b128 v[184:187], v153 offset:32768
	ds_read_b128 v[190:193], v153 offset:33792
	ds_read_b128 v[194:197], v153 offset:34816
	ds_read_b128 v[198:201], v153 offset:35840
	ds_read_b128 v[202:205], v153 offset:36864
	ds_read_b128 v[206:209], v153 offset:37888
	ds_read_b128 v[210:213], v153 offset:38912
	ds_read_b128 v[214:217], v153 offset:39936
	global_load_lds_dwordx4 v[226:227], off
	v_lshl_add_u64 v[226:227], s[26:27], 0, v[130:131]
	s_mov_b32 m0, s37
	s_nop 0
	global_load_lds_dwordx4 v[226:227], off
	s_waitcnt vmcnt(8)
	s_waitcnt lgkmcnt(0)
	s_barrier
	s_setprio 1
	v_mfma_f32_16x16x32_bf16 v[116:119], v[144:147], v[184:187], v[116:119]
	v_mfma_f32_16x16x32_bf16 v[112:115], v[160:163], v[184:187], v[112:115]
	v_mfma_f32_16x16x32_bf16 v[100:103], v[144:147], v[194:197], v[100:103]
	v_mfma_f32_16x16x32_bf16 v[96:99], v[160:163], v[194:197], v[96:99]
	v_mfma_f32_16x16x32_bf16 v[84:87], v[144:147], v[202:205], v[84:87]
	v_mfma_f32_16x16x32_bf16 v[80:83], v[160:163], v[202:205], v[80:83]
	v_mfma_f32_16x16x32_bf16 v[72:75], v[144:147], v[210:213], v[72:75]
	v_mfma_f32_16x16x32_bf16 v[64:67], v[160:163], v[210:213], v[64:67]
	v_mfma_f32_16x16x32_bf16 v[116:119], v[156:159], v[190:193], v[116:119]
	v_mfma_f32_16x16x32_bf16 v[112:115], v[164:167], v[190:193], v[112:115]
	v_mfma_f32_16x16x32_bf16 v[100:103], v[156:159], v[198:201], v[100:103]
	v_mfma_f32_16x16x32_bf16 v[96:99], v[164:167], v[198:201], v[96:99]
	v_mfma_f32_16x16x32_bf16 v[84:87], v[156:159], v[206:209], v[84:87]
	v_mfma_f32_16x16x32_bf16 v[80:83], v[164:167], v[206:209], v[80:83]
	v_mfma_f32_16x16x32_bf16 v[72:75], v[156:159], v[214:217], v[72:75]
	v_mfma_f32_16x16x32_bf16 v[64:67], v[164:167], v[214:217], v[64:67]
	v_mfma_f32_16x16x32_bf16 v[124:127], v[168:171], v[184:187], v[124:127]
	v_mfma_f32_16x16x32_bf16 v[120:123], v[176:179], v[184:187], v[120:123]
	v_mfma_f32_16x16x32_bf16 v[108:111], v[168:171], v[194:197], v[108:111]
	v_mfma_f32_16x16x32_bf16 v[104:107], v[176:179], v[194:197], v[104:107]
	v_mfma_f32_16x16x32_bf16 v[92:95], v[168:171], v[202:205], v[92:95]
	v_mfma_f32_16x16x32_bf16 v[88:91], v[176:179], v[202:205], v[88:91]
	v_mfma_f32_16x16x32_bf16 v[76:79], v[168:171], v[210:213], v[76:79]
	v_mfma_f32_16x16x32_bf16 v[68:71], v[176:179], v[210:213], v[68:71]
	v_mfma_f32_16x16x32_bf16 v[124:127], v[172:175], v[190:193], v[124:127]
	v_mfma_f32_16x16x32_bf16 v[120:123], v[180:183], v[190:193], v[120:123]
	v_mfma_f32_16x16x32_bf16 v[108:111], v[172:175], v[198:201], v[108:111]
	v_mfma_f32_16x16x32_bf16 v[104:107], v[180:183], v[198:201], v[104:107]
	v_mfma_f32_16x16x32_bf16 v[92:95], v[172:175], v[206:209], v[92:95]
	v_mfma_f32_16x16x32_bf16 v[88:91], v[180:183], v[206:209], v[88:91]
	v_mfma_f32_16x16x32_bf16 v[76:79], v[172:175], v[214:217], v[76:79]
	v_mfma_f32_16x16x32_bf16 v[68:71], v[180:183], v[214:217], v[68:71]
	s_setprio 0
	s_barrier
; #define PG8_STAGE(bufoff, gbase, voff) do { _Pragma("unroll") for (int _i = 0; _i < 2; ++_i) \
;         __builtin_amdgcn_global_load_lds((const unsigned*)((const char*)(gbase) + (voff)[_i]), (PG8_LAS unsigned*)(lds + (bufoff) + ldsw + _i * 8192), 16, 0, 0); } while (0)
; #define PG8_LDA(dst, b, h) do { _Pragma("unroll") for (int m = 0; m < 4; ++m) _Pragma("unroll") for (int k = 0; k < 2; ++k) dst[m][k] = *(const PG8_LAS bf16x8*)(lds + PG8_SA(b, h) + aoff + m * 2048 + k * 1024); } while (0)
; #define PG8_MMA(ai, bj, At, Bt) do { __builtin_amdgcn_s_setprio(1); _Pragma("unroll") for (int m = 0; m < 4; ++m) _Pragma("unroll") for (int n = 0; n < 2; ++n) _Pragma("unroll") for (int k = 0; k < 2; ++k) \
;         acc[ai][bj][m][n] = __builtin_amdgcn_mfma_f32_16x16x32_bf16(Bt[n][k], At[m][k], acc[ai][bj][m][n], 0, 0, 0); __builtin_amdgcn_s_setprio(0); } while (0)
; #define PG8_WAIT_V(n) asm volatile("s_waitcnt vmcnt(" #n ")" ::: "memory")
; #define PG8_WAIT_L(n) asm volatile("s_waitcnt lgkmcnt(" #n ")" ::: "memory")
; #define PG8_BAR __builtin_amdgcn_s_barrier()
; #define PG8_SCHED __builtin_amdgcn_sched_barrier(0)
; template <class Epi, class Sched, bool ALIGN_EPI = false, bool SP2 = false>
; __device__ __forceinline__ void gemm_phase(PG8_LAS unsigned char* lds, const Gemm g, const Sched& S, const Epi& E) {
;     ...
;         for (int t = 0; t < nt; t += 2) {
;     ...
;             PG8_LDA(At, 1, 1); PG8_STAGE(PG8_SB(1, 0), b3, voffB); PG8_STAGE(PG8_SB(1, 1), b3 + hstep, voffB); PG8_STAGE(PG8_SA(1, 0), a3, voffA);
;             PG8_WAIT_V(8); PG8_WAIT_L(0); PG8_BAR; PG8_MMA(1, 0, At, B0); PG8_MMA(1, 1, At, B1); PG8_BAR; PG8_SCHED;
	s_add_i32 s26, s52, s30
	v_lshl_add_u64 v[218:219], v[218:219], 0, s[6:7]
	s_mov_b32 m0, s26
	ds_read_b128 v[184:187], v153 offset:49152
	ds_read_b128 v[190:193], v153 offset:50176
	ds_read_b128 v[194:197], v153 offset:51200
	ds_read_b128 v[198:201], v153 offset:52224
	ds_read_b128 v[202:205], v153 offset:53248
	ds_read_b128 v[206:209], v153 offset:54272
	ds_read_b128 v[210:213], v153 offset:55296
	ds_read_b128 v[214:217], v153 offset:56320
	global_load_lds_dwordx4 v[218:219], off
	s_add_i32 m0, s26, 0x2000
	s_add_u32 s24, s24, 0x40080
	v_lshl_add_u64 v[218:219], v[220:221], 0, s[6:7]
	s_addc_u32 s25, s25, 0
	s_add_i32 s26, s53, s30
	global_load_lds_dwordx4 v[218:219], off
	v_lshl_add_u64 v[218:219], s[24:25], 0, v[132:133]
	s_mov_b32 m0, s26
	s_nop 0
	global_load_lds_dwordx4 v[218:219], off
	v_lshl_add_u64 v[218:219], s[24:25], 0, v[128:129]
	s_add_i32 m0, s26, 0x2000
	s_nop 0
	global_load_lds_dwordx4 v[218:219], off
	v_lshl_add_u64 v[218:219], v[222:223], 0, s[6:7]
	s_mov_b32 m0, s39
	s_nop 0
	global_load_lds_dwordx4 v[218:219], off
	v_lshl_add_u64 v[218:219], v[224:225], 0, s[6:7]
	s_mov_b32 m0, s40
	s_nop 0
	global_load_lds_dwordx4 v[218:219], off
	s_waitcnt vmcnt(8)
	s_waitcnt lgkmcnt(0)
	s_barrier
	s_setprio 1
	v_mfma_f32_16x16x32_bf16 v[56:59], v[144:147], v[184:187], v[56:59]
	v_mfma_f32_16x16x32_bf16 v[48:51], v[160:163], v[184:187], v[48:51]
	v_mfma_f32_16x16x32_bf16 v[40:43], v[144:147], v[194:197], v[40:43]
	v_mfma_f32_16x16x32_bf16 v[32:35], v[160:163], v[194:197], v[32:35]
	v_mfma_f32_16x16x32_bf16 v[24:27], v[144:147], v[202:205], v[24:27]
	v_mfma_f32_16x16x32_bf16 v[16:19], v[160:163], v[202:205], v[16:19]
	v_mfma_f32_16x16x32_bf16 v[8:11], v[144:147], v[210:213], v[8:11]
	v_mfma_f32_16x16x32_bf16 v[0:3], v[160:163], v[210:213], v[0:3]
	v_mfma_f32_16x16x32_bf16 v[56:59], v[156:159], v[190:193], v[56:59]
	v_mfma_f32_16x16x32_bf16 v[48:51], v[164:167], v[190:193], v[48:51]
	v_mfma_f32_16x16x32_bf16 v[40:43], v[156:159], v[198:201], v[40:43]
	v_mfma_f32_16x16x32_bf16 v[32:35], v[164:167], v[198:201], v[32:35]
	v_mfma_f32_16x16x32_bf16 v[24:27], v[156:159], v[206:209], v[24:27]
	v_mfma_f32_16x16x32_bf16 v[16:19], v[164:167], v[206:209], v[16:19]
	v_mfma_f32_16x16x32_bf16 v[8:11], v[156:159], v[214:217], v[8:11]
	v_mfma_f32_16x16x32_bf16 v[0:3], v[164:167], v[214:217], v[0:3]
	v_mfma_f32_16x16x32_bf16 v[60:63], v[168:171], v[184:187], v[60:63]
	v_mfma_f32_16x16x32_bf16 v[52:55], v[176:179], v[184:187], v[52:55]
	v_mfma_f32_16x16x32_bf16 v[44:47], v[168:171], v[194:197], v[44:47]
	v_mfma_f32_16x16x32_bf16 v[36:39], v[176:179], v[194:197], v[36:39]
	v_mfma_f32_16x16x32_bf16 v[28:31], v[168:171], v[202:205], v[28:31]
	v_mfma_f32_16x16x32_bf16 v[20:23], v[176:179], v[202:205], v[20:23]
	v_mfma_f32_16x16x32_bf16 v[12:15], v[168:171], v[210:213], v[12:15]
	v_mfma_f32_16x16x32_bf16 v[4:7], v[176:179], v[210:213], v[4:7]
	v_mfma_f32_16x16x32_bf16 v[60:63], v[172:175], v[190:193], v[60:63]
	v_mfma_f32_16x16x32_bf16 v[52:55], v[180:183], v[190:193], v[52:55]
	v_mfma_f32_16x16x32_bf16 v[44:47], v[172:175], v[198:201], v[44:47]
	v_mfma_f32_16x16x32_bf16 v[36:39], v[180:183], v[198:201], v[36:39]
	v_mfma_f32_16x16x32_bf16 v[28:31], v[172:175], v[206:209], v[28:31]
	v_mfma_f32_16x16x32_bf16 v[20:23], v[180:183], v[206:209], v[20:23]
	v_mfma_f32_16x16x32_bf16 v[12:15], v[172:175], v[214:217], v[12:15]
	v_mfma_f32_16x16x32_bf16 v[4:7], v[180:183], v[214:217], v[4:7]
	s_setprio 0
	s_barrier
	s_add_i32 s51, s51, 2
	s_add_u32 s22, s22, 0x100
	s_addc_u32 s23, s23, 0
	s_add_u32 s49, s49, 0x100
	s_addc_u32 s50, s50, 0
	s_branch .LBB0_782

; __device__ __forceinline__ unsigned pk2(float lo, float hi) { return pg8::cvt_pk_bf16(lo, hi); }
; __device__ __forceinline__ float silu_f(float x) { return x * sigmoid_f(x); }
;     __device__ __forceinline__ void operator()(const f32x4 (&acc)[2][2][4][2], const pg8::Unit& u, int wr, int wc, int fr, int fq) const {
;         const int row0 = u.pm * 256 + wr * 64 + fr, col = u.pn * 128 + wc * 32 + 8 * fq;
; #pragma unroll
;         for (int ai = 0; ai < 2; ++ai)
; #pragma unroll
;             for (int m = 0; m < 4; ++m) {
;                 const int row = row0 + ai * 128 + m * 16;
;                 const float rs = sumsq ? rsqrtf(sumsq[row] * (1.f / 1024.f) + EPS) : 1.f;
;                 float o[8];
; #pragma unroll
;                 for (int n = 0; n < 2; ++n)
; #pragma unroll
;                     for (int e = 0; e < 4; ++e) { const float g = acc[ai][0][m][n][e] * rs, up = acc[ai][1][m][n][e] * rs; o[4 * n + e] = silu_f(g) * up; }
;                 u32x4 w; w.x = pk2(o[0], o[1]); w.y = pk2(o[2], o[3]); w.z = pk2(o[4], o[5]); w.w = pk2(o[6], o[7]);
;                 *(u32x4*)(H + (size_t)row * DFF + col) = w;
.LBB0_785:
	v_lshl_add_u32 v144, s0, 8, v148
	v_mov_b32_e32 v228, v144
	v_ashrrev_i32_e32 v145, 31, v144
	v_lshl_add_u64 v[146:147], v[144:145], 2, s[10:11]
	global_load_dword v145, v[146:147], off
	global_load_dword v236, v[146:147], off offset:64
	global_load_dword v237, v[146:147], off offset:128
	global_load_dword v238, v[146:147], off offset:192
	global_load_dword v239, v[146:147], off offset:512
	global_load_dword v240, v[146:147], off offset:576
	global_load_dword v241, v[146:147], off offset:640
	global_load_dword v242, v[146:147], off offset:704
	v_lshl_or_b32 v156, s1, 7, v150
	v_readlane_b32 s0, v235, 33
	v_mov_b32_e32 v161, v114
	v_mov_b32_e32 v114, v123
	v_readlane_b32 s1, v235, 34
	v_mov_b32_e32 v158, v124
	v_mov_b32_e32 v159, v116
	v_mov_b32_e32 v116, v125
	v_mov_b32_e32 v124, v126
	v_mov_b32_e32 v125, v118
	v_mov_b32_e32 v118, v127
	v_mov_b32_e32 v126, v120
	v_mov_b32_e32 v127, v112
	v_mov_b32_e32 v112, v121
	v_mov_b32_e32 v160, v122
	v_mov_b64_e32 v[120:121], s[0:1]
	v_ashrrev_i32_e32 v157, 31, v156
	v_or_b32_e32 v164, 16, v144
	v_mad_i64_i32 v[162:163], s[0:1], v144, s46, v[120:121]
	v_lshlrev_b64 v[122:123], 1, v[156:157]
	v_ashrrev_i32_e32 v165, 31, v164
	v_lshl_add_u64 v[156:157], v[162:163], 0, v[122:123]
	v_lshl_add_u64 v[162:163], v[164:165], 2, s[10:11]
	s_waitcnt vmcnt(0)
	v_fmamk_f32 v145, v145, 0x3a800000, v154
	v_mul_f32_e32 v155, 0x4b800000, v145
	v_cmp_gt_f32_e32 vcc, s45, v145
	s_nop 1
	v_cndmask_b32_e32 v145, v145, v155, vcc
	v_rsq_f32_e32 v145, v145
	s_nop 0
	v_mul_f32_e32 v155, 0x45800000, v145
	v_cndmask_b32_e32 v166, v145, v155, vcc
	v_pk_mul_f32 v[114:115], v[114:115], v[166:167] op_sel_hi:[1,0]
	v_pk_mul_f32 v[158:159], v[158:159], v[166:167] op_sel_hi:[1,0]
	v_pk_mul_f32 v[116:117], v[116:117], v[166:167] op_sel_hi:[1,0]
	v_pk_mul_f32 v[124:125], v[124:125], v[166:167] op_sel_hi:[1,0]
	v_pk_mul_f32 v[118:119], v[118:119], v[166:167] op_sel_hi:[1,0]
	v_pk_mul_f32 v[126:127], v[126:127], v[166:167] op_sel_hi:[1,0]
	v_pk_mul_f32 v[112:113], v[112:113], v[166:167] op_sel_hi:[1,0]
	v_pk_mul_f32 v[160:161], v[160:161], v[166:167] op_sel_hi:[1,0]
	v_mul_f32_e32 v170, 0xbfb8aa3b, v115
	v_mul_f32_e32 v145, 0xbfb8aa3b, v159
	v_mul_f32_e32 v155, 0xbfb8aa3b, v117
	v_mul_f32_e32 v165, 0xbfb8aa3b, v125
	v_mul_f32_e32 v166, 0xbfb8aa3b, v119
	v_mul_f32_e32 v167, 0xbfb8aa3b, v127
	v_mul_f32_e32 v168, 0xbfb8aa3b, v113
	v_mul_f32_e32 v169, 0xbfb8aa3b, v161
	v_exp_f32_e32 v170, v170
	v_exp_f32_e32 v145, v145
	v_exp_f32_e32 v155, v155
	v_exp_f32_e32 v165, v165
	v_exp_f32_e32 v166, v166
	v_exp_f32_e32 v167, v167
	v_exp_f32_e32 v168, v168
	v_exp_f32_e32 v169, v169
	v_add_f32_e32 v170, 1.0, v170
	v_add_f32_e32 v145, 1.0, v145
	v_add_f32_e32 v155, 1.0, v155
	v_add_f32_e32 v165, 1.0, v165
	v_add_f32_e32 v166, 1.0, v166
	v_add_f32_e32 v167, 1.0, v167
	v_add_f32_e32 v168, 1.0, v168
	v_add_f32_e32 v169, 1.0, v169
	v_rcp_f32_e32 v170, v170
	v_rcp_f32_e32 v145, v145
	v_rcp_f32_e32 v155, v155
	v_rcp_f32_e32 v165, v165
	v_rcp_f32_e32 v166, v166
	v_rcp_f32_e32 v167, v167
	v_rcp_f32_e32 v168, v168
	v_rcp_f32_e32 v169, v169
	v_mul_f32_e32 v115, v115, v170
	v_mul_f32_e32 v145, v159, v145
	v_mul_f32_e32 v117, v117, v155
	v_mul_f32_e32 v125, v125, v165
	v_mul_f32_e32 v119, v119, v166
	v_mul_f32_e32 v127, v127, v167
	v_mul_f32_e32 v113, v113, v168
	v_mul_f32_e32 v155, v161, v169
	v_mul_f32_e32 v115, v114, v115
	v_mul_f32_e32 v145, v158, v145
	v_mul_f32_e32 v116, v116, v117
	v_mul_f32_e32 v117, v124, v125
	v_mul_f32_e32 v118, v118, v119
	v_mul_f32_e32 v119, v126, v127
	v_mul_f32_e32 v124, v112, v113
	v_mul_f32_e32 v125, v160, v155
	v_cvt_pk_bf16_f32 v112, v145, v116
	v_cvt_pk_bf16_f32 v113, v117, v118
	v_cvt_pk_bf16_f32 v114, v119, v124
	v_cvt_pk_bf16_f32 v115, v125, v115
	global_store_dwordx4 v[156:157], v[112:115], off
	s_nop 0
	s_nop 0
	v_mov_b32_e32 v113, v100
	v_mov_b32_e32 v100, v109
	v_mov_b32_e32 v109, v102
	v_mov_b32_e32 v102, v111
	v_mov_b32_e32 v111, v96
	v_mov_b32_e32 v96, v105
	v_mov_b32_e32 v105, v98
	v_mov_b32_e32 v98, v107
	v_mov_b32_e32 v112, v108
	v_mov_b32_e32 v108, v110
	v_mov_b32_e32 v110, v104
	v_mov_b32_e32 v104, v106
	v_or_b32_e32 v106, 32, v144
	v_mad_i64_i32 v[114:115], s[0:1], v164, s46, v[120:121]
	v_lshl_add_u64 v[114:115], v[114:115], 0, v[122:123]
	s_nop 0
	v_fmamk_f32 v107, v236, 0x3a800000, v154
	v_mul_f32_e32 v116, 0x4b800000, v107
	v_cmp_gt_f32_e32 vcc, s45, v107
	s_nop 1
	v_cndmask_b32_e32 v107, v107, v116, vcc
	v_rsq_f32_e32 v118, v107
	v_ashrrev_i32_e32 v107, 31, v106
	v_lshl_add_u64 v[116:117], v[106:107], 2, s[10:11]
	v_mul_f32_e32 v107, 0x45800000, v118
	v_cndmask_b32_e32 v118, v118, v107, vcc
	v_pk_mul_f32 v[98:99], v[98:99], v[118:119] op_sel_hi:[1,0]
	v_pk_mul_f32 v[112:113], v[112:113], v[118:119] op_sel_hi:[1,0]
	v_pk_mul_f32 v[100:101], v[100:101], v[118:119] op_sel_hi:[1,0]
	v_pk_mul_f32 v[108:109], v[108:109], v[118:119] op_sel_hi:[1,0]
	v_pk_mul_f32 v[102:103], v[102:103], v[118:119] op_sel_hi:[1,0]
	v_pk_mul_f32 v[110:111], v[110:111], v[118:119] op_sel_hi:[1,0]
	v_pk_mul_f32 v[96:97], v[96:97], v[118:119] op_sel_hi:[1,0]
	v_pk_mul_f32 v[104:105], v[104:105], v[118:119] op_sel_hi:[1,0]
	v_mul_f32_e32 v145, 0xbfb8aa3b, v99
	v_mul_f32_e32 v107, 0xbfb8aa3b, v113
	v_mul_f32_e32 v118, 0xbfb8aa3b, v101
	v_mul_f32_e32 v119, 0xbfb8aa3b, v109
	v_mul_f32_e32 v124, 0xbfb8aa3b, v103
	v_mul_f32_e32 v125, 0xbfb8aa3b, v111
	v_mul_f32_e32 v126, 0xbfb8aa3b, v97
	v_mul_f32_e32 v127, 0xbfb8aa3b, v105
	v_exp_f32_e32 v145, v145
	v_exp_f32_e32 v107, v107
	v_exp_f32_e32 v118, v118
	v_exp_f32_e32 v119, v119
	v_exp_f32_e32 v124, v124
	v_exp_f32_e32 v125, v125
	v_exp_f32_e32 v126, v126
	v_exp_f32_e32 v127, v127
; __device__ __forceinline__ unsigned pk2(float lo, float hi) { return pg8::cvt_pk_bf16(lo, hi); }
; __device__ __forceinline__ float silu_f(float x) { return x * sigmoid_f(x); }
;     __device__ __forceinline__ void operator()(const f32x4 (&acc)[2][2][4][2], const pg8::Unit& u, int wr, int wc, int fr, int fq) const {
;         const int row0 = u.pm * 256 + wr * 64 + fr, col = u.pn * 128 + wc * 32 + 8 * fq;
; #pragma unroll
;         for (int ai = 0; ai < 2; ++ai)
; #pragma unroll
;             for (int m = 0; m < 4; ++m) {
;                 const int row = row0 + ai * 128 + m * 16;
;                 const float rs = sumsq ? rsqrtf(sumsq[row] * (1.f / 1024.f) + EPS) : 1.f;
;                 float o[8];
; #pragma unroll
;                 for (int n = 0; n < 2; ++n)
; #pragma unroll
;                     for (int e = 0; e < 4; ++e) { const float g = acc[ai][0][m][n][e] * rs, up = acc[ai][1][m][n][e] * rs; o[4 * n + e] = silu_f(g) * up; }
;                 u32x4 w; w.x = pk2(o[0], o[1]); w.y = pk2(o[2], o[3]); w.z = pk2(o[4], o[5]); w.w = pk2(o[6], o[7]);
;                 *(u32x4*)(H + (size_t)row * DFF + col) = w;
	v_add_f32_e32 v145, 1.0, v145
	v_add_f32_e32 v107, 1.0, v107
	v_add_f32_e32 v118, 1.0, v118
	v_add_f32_e32 v119, 1.0, v119
	v_add_f32_e32 v124, 1.0, v124
	v_add_f32_e32 v125, 1.0, v125
	v_add_f32_e32 v126, 1.0, v126
	v_add_f32_e32 v127, 1.0, v127
	v_rcp_f32_e32 v145, v145
	v_rcp_f32_e32 v107, v107
	v_rcp_f32_e32 v118, v118
	v_rcp_f32_e32 v119, v119
	v_rcp_f32_e32 v124, v124
	v_rcp_f32_e32 v125, v125
	v_rcp_f32_e32 v126, v126
	v_rcp_f32_e32 v127, v127
	v_mul_f32_e32 v99, v99, v145
	v_mul_f32_e32 v107, v113, v107
	v_mul_f32_e32 v101, v101, v118
	v_mul_f32_e32 v109, v109, v119
	v_mul_f32_e32 v103, v103, v124
	v_mul_f32_e32 v111, v111, v125
	v_mul_f32_e32 v97, v97, v126
	v_mul_f32_e32 v105, v105, v127
	v_mul_f32_e32 v99, v98, v99
	v_mul_f32_e32 v107, v112, v107
	v_mul_f32_e32 v100, v100, v101
	v_mul_f32_e32 v101, v108, v109
	v_mul_f32_e32 v102, v102, v103
	v_mul_f32_e32 v103, v110, v111
	v_mul_f32_e32 v108, v96, v97
	v_mul_f32_e32 v104, v104, v105
	v_cvt_pk_bf16_f32 v96, v107, v100
	v_cvt_pk_bf16_f32 v97, v101, v102
	v_cvt_pk_bf16_f32 v98, v103, v108
	v_cvt_pk_bf16_f32 v99, v104, v99
	global_store_dwordx4 v[114:115], v[96:99], off
	s_nop 0
	s_nop 0
	v_mov_b32_e32 v97, v84
	v_mov_b32_e32 v84, v93
	v_mov_b32_e32 v93, v86
	v_mov_b32_e32 v86, v95
	v_mov_b32_e32 v95, v80
	v_mov_b32_e32 v80, v89
	v_mov_b32_e32 v89, v82
	v_mov_b32_e32 v82, v91
	v_mov_b32_e32 v96, v92
	v_mov_b32_e32 v92, v94
	v_mov_b32_e32 v94, v88
	v_mov_b32_e32 v88, v90
	v_or_b32_e32 v90, 48, v144
	v_mad_i64_i32 v[98:99], s[0:1], v106, s46, v[120:121]
	v_lshl_add_u64 v[98:99], v[98:99], 0, v[122:123]
	s_nop 0
	v_fmamk_f32 v91, v237, 0x3a800000, v154
	v_mul_f32_e32 v100, 0x4b800000, v91
	v_cmp_gt_f32_e32 vcc, s45, v91
	s_nop 1
	v_cndmask_b32_e32 v91, v91, v100, vcc
	v_rsq_f32_e32 v102, v91
	v_ashrrev_i32_e32 v91, 31, v90
	v_lshl_add_u64 v[100:101], v[90:91], 2, s[10:11]
	v_mul_f32_e32 v91, 0x45800000, v102
	v_cndmask_b32_e32 v102, v102, v91, vcc
	v_pk_mul_f32 v[82:83], v[82:83], v[102:103] op_sel_hi:[1,0]
	v_pk_mul_f32 v[96:97], v[96:97], v[102:103] op_sel_hi:[1,0]
	v_pk_mul_f32 v[84:85], v[84:85], v[102:103] op_sel_hi:[1,0]
	v_pk_mul_f32 v[92:93], v[92:93], v[102:103] op_sel_hi:[1,0]
	v_pk_mul_f32 v[86:87], v[86:87], v[102:103] op_sel_hi:[1,0]
	v_pk_mul_f32 v[94:95], v[94:95], v[102:103] op_sel_hi:[1,0]
	v_pk_mul_f32 v[80:81], v[80:81], v[102:103] op_sel_hi:[1,0]
	v_pk_mul_f32 v[88:89], v[88:89], v[102:103] op_sel_hi:[1,0]
	v_mul_f32_e32 v108, 0xbfb8aa3b, v83
	v_mul_f32_e32 v91, 0xbfb8aa3b, v97
	v_mul_f32_e32 v102, 0xbfb8aa3b, v85
	v_mul_f32_e32 v103, 0xbfb8aa3b, v93
	v_mul_f32_e32 v104, 0xbfb8aa3b, v87
	v_mul_f32_e32 v105, 0xbfb8aa3b, v95
	v_mul_f32_e32 v106, 0xbfb8aa3b, v81
	v_mul_f32_e32 v107, 0xbfb8aa3b, v89
	v_exp_f32_e32 v108, v108
	v_exp_f32_e32 v91, v91
	v_exp_f32_e32 v102, v102
	v_exp_f32_e32 v103, v103
	v_exp_f32_e32 v104, v104
	v_exp_f32_e32 v105, v105
	v_exp_f32_e32 v106, v106
	v_exp_f32_e32 v107, v107
	v_add_f32_e32 v108, 1.0, v108
	v_add_f32_e32 v91, 1.0, v91
	v_add_f32_e32 v102, 1.0, v102
	v_add_f32_e32 v103, 1.0, v103
	v_add_f32_e32 v104, 1.0, v104
	v_add_f32_e32 v105, 1.0, v105
	v_add_f32_e32 v106, 1.0, v106
	v_add_f32_e32 v107, 1.0, v107
	v_rcp_f32_e32 v108, v108
	v_rcp_f32_e32 v91, v91
	v_rcp_f32_e32 v102, v102
	v_rcp_f32_e32 v103, v103
	v_rcp_f32_e32 v104, v104
	v_rcp_f32_e32 v105, v105
	v_rcp_f32_e32 v106, v106
	v_rcp_f32_e32 v107, v107
	v_mul_f32_e32 v83, v83, v108
	v_mul_f32_e32 v91, v97, v91
	v_mul_f32_e32 v85, v85, v102
	v_mul_f32_e32 v93, v93, v103
	v_mul_f32_e32 v87, v87, v104
	v_mul_f32_e32 v95, v95, v105
	v_mul_f32_e32 v81, v81, v106
	v_mul_f32_e32 v89, v89, v107
	v_mul_f32_e32 v83, v82, v83
	v_mul_f32_e32 v91, v96, v91
	v_mul_f32_e32 v84, v84, v85
	v_mul_f32_e32 v85, v92, v93
	v_mul_f32_e32 v86, v86, v87
	v_mul_f32_e32 v87, v94, v95
	v_mul_f32_e32 v92, v80, v81
	v_mul_f32_e32 v88, v88, v89
	v_cvt_pk_bf16_f32 v80, v91, v84
	v_cvt_pk_bf16_f32 v81, v85, v86
	v_cvt_pk_bf16_f32 v82, v87, v92
	v_cvt_pk_bf16_f32 v83, v88, v83
	global_store_dwordx4 v[98:99], v[80:83], off
	s_nop 0
	s_nop 0
	v_mov_b32_e32 v80, v76
	v_mov_b32_e32 v76, v78
	v_mov_b32_e32 v78, v68
	v_mov_b32_e32 v68, v70
	v_mov_b32_e32 v81, v72
	v_mov_b32_e32 v72, v77
	v_mov_b32_e32 v77, v74
	v_mov_b32_e32 v74, v79
	v_mov_b32_e32 v79, v64
	v_mov_b32_e32 v64, v69
	v_mov_b32_e32 v69, v66
	v_mov_b32_e32 v66, v71
	s_nop 0
	v_fmamk_f32 v70, v238, 0x3a800000, v154
	v_mul_f32_e32 v71, 0x4b800000, v70
	v_cmp_gt_f32_e32 vcc, s45, v70
	s_nop 1
	v_cndmask_b32_e32 v70, v70, v71, vcc
	v_rsq_f32_e32 v82, v70
	v_mad_i64_i32 v[70:71], s[0:1], v90, s46, v[120:121]
	v_lshl_add_u64 v[70:71], v[70:71], 0, v[122:123]
	v_mul_f32_e32 v83, 0x45800000, v82
	v_cndmask_b32_e32 v82, v82, v83, vcc
	v_pk_mul_f32 v[66:67], v[66:67], v[82:83] op_sel_hi:[1,0]
	v_pk_mul_f32 v[80:81], v[80:81], v[82:83] op_sel_hi:[1,0]
	v_pk_mul_f32 v[72:73], v[72:73], v[82:83] op_sel_hi:[1,0]
	v_pk_mul_f32 v[76:77], v[76:77], v[82:83] op_sel_hi:[1,0]
	v_pk_mul_f32 v[74:75], v[74:75], v[82:83] op_sel_hi:[1,0]
	v_pk_mul_f32 v[78:79], v[78:79], v[82:83] op_sel_hi:[1,0]
	v_pk_mul_f32 v[64:65], v[64:65], v[82:83] op_sel_hi:[1,0]
	v_pk_mul_f32 v[68:69], v[68:69], v[82:83] op_sel_hi:[1,0]
	v_mul_f32_e32 v89, 0xbfb8aa3b, v67
	v_mul_f32_e32 v82, 0xbfb8aa3b, v81
	v_mul_f32_e32 v83, 0xbfb8aa3b, v73
	v_mul_f32_e32 v84, 0xbfb8aa3b, v77
	v_mul_f32_e32 v85, 0xbfb8aa3b, v75
	v_mul_f32_e32 v86, 0xbfb8aa3b, v79
	v_mul_f32_e32 v87, 0xbfb8aa3b, v65
	v_mul_f32_e32 v88, 0xbfb8aa3b, v69
	v_exp_f32_e32 v89, v89
	v_exp_f32_e32 v82, v82
	v_exp_f32_e32 v83, v83
	v_exp_f32_e32 v84, v84
	v_exp_f32_e32 v85, v85
	v_exp_f32_e32 v86, v86
	v_exp_f32_e32 v87, v87
	v_exp_f32_e32 v88, v88
; #define PG8_BAR __builtin_amdgcn_s_barrier()
; __device__ __forceinline__ unsigned pk2(float lo, float hi) { return pg8::cvt_pk_bf16(lo, hi); }
; __device__ __forceinline__ float silu_f(float x) { return x * sigmoid_f(x); }
; template <class Epi, class Sched, bool ALIGN_EPI = false, bool SP2 = false>
; __device__ __forceinline__ void gemm_phase(PG8_LAS unsigned char* lds, const Gemm g, const Sched& S, const Epi& E) {
;     ...
;         if constexpr (!Epi::AFTER_DRAIN) { E(acc, cur, wr, wc, fr, fq); S.done(cur); }
;         if (!has_next) break;
; #pragma unroll
;         for (int a = 0; a < 2; ++a)
; #pragma unroll
;             for (int b = 0; b < 2; ++b)
; #pragma unroll
;                 for (int m = 0; m < 4; ++m)
; #pragma unroll
;                     for (int n = 0; n < 2; ++n) acc[a][b][m][n] = (f32x4){0.f, 0.f, 0.f, 0.f};
;         cur = nxt; cA = nA; cB = nB; ++ui;
;         if constexpr (ALIGN_EPI) { if (wr == 1) PG8_BAR; }
;     }
;     __device__ __forceinline__ void operator()(const f32x4 (&acc)[2][2][4][2], const pg8::Unit& u, int wr, int wc, int fr, int fq) const {
;         const int row0 = u.pm * 256 + wr * 64 + fr, col = u.pn * 128 + wc * 32 + 8 * fq;
; #pragma unroll
;         for (int ai = 0; ai < 2; ++ai)
; #pragma unroll
;             for (int m = 0; m < 4; ++m) {
;                 const int row = row0 + ai * 128 + m * 16;
;                 const float rs = sumsq ? rsqrtf(sumsq[row] * (1.f / 1024.f) + EPS) : 1.f;
;                 float o[8];
; #pragma unroll
;                 for (int n = 0; n < 2; ++n)
; #pragma unroll
;                     for (int e = 0; e < 4; ++e) { const float g = acc[ai][0][m][n][e] * rs, up = acc[ai][1][m][n][e] * rs; o[4 * n + e] = silu_f(g) * up; }
;                 u32x4 w; w.x = pk2(o[0], o[1]); w.y = pk2(o[2], o[3]); w.z = pk2(o[4], o[5]); w.w = pk2(o[6], o[7]);
;                 *(u32x4*)(H + (size_t)row * DFF + col) = w;
	v_add_f32_e32 v89, 1.0, v89
	v_add_f32_e32 v82, 1.0, v82
	v_add_f32_e32 v83, 1.0, v83
	v_add_f32_e32 v84, 1.0, v84
	v_add_f32_e32 v85, 1.0, v85
	v_add_f32_e32 v86, 1.0, v86
	v_add_f32_e32 v87, 1.0, v87
	v_add_f32_e32 v88, 1.0, v88
	v_rcp_f32_e32 v89, v89
	v_rcp_f32_e32 v82, v82
	v_rcp_f32_e32 v83, v83
	v_rcp_f32_e32 v84, v84
	v_rcp_f32_e32 v85, v85
	v_rcp_f32_e32 v86, v86
	v_rcp_f32_e32 v87, v87
	v_rcp_f32_e32 v88, v88
	v_mul_f32_e32 v67, v67, v89
	v_mul_f32_e32 v81, v81, v82
	v_mul_f32_e32 v73, v73, v83
	v_mul_f32_e32 v77, v77, v84
	v_mul_f32_e32 v75, v75, v85
	v_mul_f32_e32 v79, v79, v86
	v_mul_f32_e32 v65, v65, v87
	v_mul_f32_e32 v69, v69, v88
	v_mul_f32_e32 v67, v66, v67
	v_mul_f32_e32 v80, v80, v81
	v_mul_f32_e32 v72, v72, v73
	v_mul_f32_e32 v73, v76, v77
	v_mul_f32_e32 v74, v74, v75
	v_mul_f32_e32 v75, v78, v79
	v_mul_f32_e32 v76, v64, v65
	v_mul_f32_e32 v68, v68, v69
	v_cvt_pk_bf16_f32 v64, v80, v72
	v_cvt_pk_bf16_f32 v65, v73, v74
	v_cvt_pk_bf16_f32 v66, v75, v76
	v_cvt_pk_bf16_f32 v67, v68, v67
	global_store_dwordx4 v[70:71], v[64:67], off
	s_nop 0
	s_nop 0
	v_mov_b32_e32 v65, v56
	v_mov_b32_e32 v56, v61
	v_mov_b32_e32 v61, v58
	v_mov_b32_e32 v58, v63
	v_mov_b32_e32 v63, v48
	v_mov_b32_e32 v48, v53
	v_mov_b32_e32 v53, v50
	v_mov_b32_e32 v50, v55
	v_mov_b32_e32 v64, v60
	v_mov_b32_e32 v60, v62
	v_mov_b32_e32 v62, v52
	v_mov_b32_e32 v52, v54
	v_add_u32_e32 v54, 0x80, v144
	s_nop 0
	v_fmamk_f32 v55, v239, 0x3a800000, v154
	v_mul_f32_e32 v66, 0x4b800000, v55
	v_cmp_gt_f32_e32 vcc, s45, v55
	s_nop 1
	v_cndmask_b32_e32 v55, v55, v66, vcc
	v_rsq_f32_e32 v66, v55
	v_mad_i64_i32 v[54:55], s[0:1], v54, s46, v[120:121]
	v_lshl_add_u64 v[54:55], v[54:55], 0, v[122:123]
	v_mul_f32_e32 v67, 0x45800000, v66
	v_cndmask_b32_e32 v66, v66, v67, vcc
	v_pk_mul_f32 v[50:51], v[50:51], v[66:67] op_sel_hi:[1,0]
	v_pk_mul_f32 v[64:65], v[64:65], v[66:67] op_sel_hi:[1,0]
	v_pk_mul_f32 v[56:57], v[56:57], v[66:67] op_sel_hi:[1,0]
	v_pk_mul_f32 v[60:61], v[60:61], v[66:67] op_sel_hi:[1,0]
	v_pk_mul_f32 v[58:59], v[58:59], v[66:67] op_sel_hi:[1,0]
	v_pk_mul_f32 v[62:63], v[62:63], v[66:67] op_sel_hi:[1,0]
	v_pk_mul_f32 v[48:49], v[48:49], v[66:67] op_sel_hi:[1,0]
	v_pk_mul_f32 v[52:53], v[52:53], v[66:67] op_sel_hi:[1,0]
	v_mul_f32_e32 v73, 0xbfb8aa3b, v51
	v_mul_f32_e32 v66, 0xbfb8aa3b, v65
	v_mul_f32_e32 v67, 0xbfb8aa3b, v57
	v_mul_f32_e32 v68, 0xbfb8aa3b, v61
	v_mul_f32_e32 v69, 0xbfb8aa3b, v59
	v_mul_f32_e32 v70, 0xbfb8aa3b, v63
	v_mul_f32_e32 v71, 0xbfb8aa3b, v49
	v_mul_f32_e32 v72, 0xbfb8aa3b, v53
	v_exp_f32_e32 v73, v73
	v_exp_f32_e32 v66, v66
	v_exp_f32_e32 v67, v67
	v_exp_f32_e32 v68, v68
	v_exp_f32_e32 v69, v69
	v_exp_f32_e32 v70, v70
	v_exp_f32_e32 v71, v71
	v_exp_f32_e32 v72, v72
	v_add_f32_e32 v73, 1.0, v73
	v_add_f32_e32 v66, 1.0, v66
	v_add_f32_e32 v67, 1.0, v67
	v_add_f32_e32 v68, 1.0, v68
	v_add_f32_e32 v69, 1.0, v69
	v_add_f32_e32 v70, 1.0, v70
	v_add_f32_e32 v71, 1.0, v71
	v_add_f32_e32 v72, 1.0, v72
	v_rcp_f32_e32 v73, v73
	v_rcp_f32_e32 v66, v66
	v_rcp_f32_e32 v67, v67
	v_rcp_f32_e32 v68, v68
	v_rcp_f32_e32 v69, v69
	v_rcp_f32_e32 v70, v70
	v_rcp_f32_e32 v71, v71
	v_rcp_f32_e32 v72, v72
	v_mul_f32_e32 v51, v51, v73
	v_mul_f32_e32 v65, v65, v66
	v_mul_f32_e32 v57, v57, v67
	v_mul_f32_e32 v61, v61, v68
	v_mul_f32_e32 v59, v59, v69
	v_mul_f32_e32 v63, v63, v70
	v_mul_f32_e32 v49, v49, v71
	v_mul_f32_e32 v53, v53, v72
	v_mul_f32_e32 v51, v50, v51
	v_mul_f32_e32 v64, v64, v65
	v_mul_f32_e32 v56, v56, v57
	v_mul_f32_e32 v57, v60, v61
	v_mul_f32_e32 v58, v58, v59
	v_mul_f32_e32 v59, v62, v63
	v_mul_f32_e32 v60, v48, v49
	v_mul_f32_e32 v52, v52, v53
	v_cvt_pk_bf16_f32 v48, v64, v56
	v_cvt_pk_bf16_f32 v49, v57, v58
	v_cvt_pk_bf16_f32 v50, v59, v60
	v_cvt_pk_bf16_f32 v51, v52, v51
	global_store_dwordx4 v[54:55], v[48:51], off
	s_nop 0
	s_nop 0
	v_mov_b32_e32 v49, v40
	v_mov_b32_e32 v40, v45
	v_mov_b32_e32 v45, v42
	v_mov_b32_e32 v42, v47
	v_mov_b32_e32 v47, v32
	v_mov_b32_e32 v32, v37
	v_mov_b32_e32 v37, v34
	v_mov_b32_e32 v34, v39
	v_mov_b32_e32 v48, v44
	v_mov_b32_e32 v44, v46
	v_mov_b32_e32 v46, v36
	v_mov_b32_e32 v36, v38
	v_add_u32_e32 v38, 0x90, v144
	s_nop 0
	v_fmamk_f32 v39, v240, 0x3a800000, v154
	v_mul_f32_e32 v50, 0x4b800000, v39
	v_cmp_gt_f32_e32 vcc, s45, v39
	s_nop 1
	v_cndmask_b32_e32 v39, v39, v50, vcc
	v_rsq_f32_e32 v50, v39
	v_mad_i64_i32 v[38:39], s[0:1], v38, s46, v[120:121]
	v_lshl_add_u64 v[38:39], v[38:39], 0, v[122:123]
	v_mul_f32_e32 v51, 0x45800000, v50
	v_cndmask_b32_e32 v50, v50, v51, vcc
	v_pk_mul_f32 v[34:35], v[34:35], v[50:51] op_sel_hi:[1,0]
	v_pk_mul_f32 v[48:49], v[48:49], v[50:51] op_sel_hi:[1,0]
	v_pk_mul_f32 v[40:41], v[40:41], v[50:51] op_sel_hi:[1,0]
	v_pk_mul_f32 v[44:45], v[44:45], v[50:51] op_sel_hi:[1,0]
	v_pk_mul_f32 v[42:43], v[42:43], v[50:51] op_sel_hi:[1,0]
	v_pk_mul_f32 v[46:47], v[46:47], v[50:51] op_sel_hi:[1,0]
	v_pk_mul_f32 v[32:33], v[32:33], v[50:51] op_sel_hi:[1,0]
	v_pk_mul_f32 v[36:37], v[36:37], v[50:51] op_sel_hi:[1,0]
	v_mul_f32_e32 v57, 0xbfb8aa3b, v35
	v_mul_f32_e32 v50, 0xbfb8aa3b, v49
	v_mul_f32_e32 v51, 0xbfb8aa3b, v41
	v_mul_f32_e32 v52, 0xbfb8aa3b, v45
	v_mul_f32_e32 v53, 0xbfb8aa3b, v43
	v_mul_f32_e32 v54, 0xbfb8aa3b, v47
	v_mul_f32_e32 v55, 0xbfb8aa3b, v33
	v_mul_f32_e32 v56, 0xbfb8aa3b, v37
	v_exp_f32_e32 v57, v57
	v_exp_f32_e32 v50, v50
	v_exp_f32_e32 v51, v51
	v_exp_f32_e32 v52, v52
	v_exp_f32_e32 v53, v53
	v_exp_f32_e32 v54, v54
	v_exp_f32_e32 v55, v55
	v_exp_f32_e32 v56, v56
	v_add_f32_e32 v57, 1.0, v57
	v_add_f32_e32 v50, 1.0, v50
	v_add_f32_e32 v51, 1.0, v51
	v_add_f32_e32 v52, 1.0, v52
	v_add_f32_e32 v53, 1.0, v53
	v_add_f32_e32 v54, 1.0, v54
	v_add_f32_e32 v55, 1.0, v55
	v_add_f32_e32 v56, 1.0, v56
	v_rcp_f32_e32 v57, v57
	v_rcp_f32_e32 v50, v50
	v_rcp_f32_e32 v51, v51
	v_rcp_f32_e32 v52, v52
	v_rcp_f32_e32 v53, v53
	v_rcp_f32_e32 v54, v54
	v_rcp_f32_e32 v55, v55
	v_rcp_f32_e32 v56, v56
	v_mul_f32_e32 v35, v35, v57
	v_mul_f32_e32 v49, v49, v50
	v_mul_f32_e32 v41, v41, v51
	v_mul_f32_e32 v45, v45, v52
	v_mul_f32_e32 v43, v43, v53
	v_mul_f32_e32 v47, v47, v54
	v_mul_f32_e32 v33, v33, v55
	v_mul_f32_e32 v37, v37, v56
	v_mul_f32_e32 v35, v34, v35
	v_mul_f32_e32 v48, v48, v49
	v_mul_f32_e32 v40, v40, v41
	v_mul_f32_e32 v41, v44, v45
	v_mul_f32_e32 v42, v42, v43
	v_mul_f32_e32 v43, v46, v47
	v_mul_f32_e32 v44, v32, v33
	v_mul_f32_e32 v36, v36, v37
	v_cvt_pk_bf16_f32 v32, v48, v40
	v_cvt_pk_bf16_f32 v33, v41, v42
	v_cvt_pk_bf16_f32 v34, v43, v44
	v_cvt_pk_bf16_f32 v35, v36, v35
	global_store_dwordx4 v[38:39], v[32:35], off
	s_andn2_b64 vcc, exec, s[4:5]
	s_mov_b64 s[0:1], -1
	s_mov_b32 s98, 1
	s_cbranch_vccnz .LBB0_778
	s_andn2_b64 vcc, exec, s[2:3]
	s_cbranch_vccnz .LBB0_777
	s_barrier
	s_branch .LBB0_777
; __device__ __forceinline__ unsigned pk2(float lo, float hi) { return pg8::cvt_pk_bf16(lo, hi); }
; __device__ __forceinline__ float silu_f(float x) { return x * sigmoid_f(x); }
;     __device__ __forceinline__ void operator()(const f32x4 (&acc)[2][2][4][2], const pg8::Unit& u, int wr, int wc, int fr, int fq) const {
;         const int row0 = u.pm * 256 + wr * 64 + fr, col = u.pn * 128 + wc * 32 + 8 * fq;
; #pragma unroll
;         for (int ai = 0; ai < 2; ++ai)
; #pragma unroll
;             for (int m = 0; m < 4; ++m) {
;                 const int row = row0 + ai * 128 + m * 16;
;                 const float rs = sumsq ? rsqrtf(sumsq[row] * (1.f / 1024.f) + EPS) : 1.f;
;                 float o[8];
; #pragma unroll
;                 for (int n = 0; n < 2; ++n)
; #pragma unroll
;                     for (int e = 0; e < 4; ++e) { const float g = acc[ai][0][m][n][e] * rs, up = acc[ai][1][m][n][e] * rs; o[4 * n + e] = silu_f(g) * up; }
;                 u32x4 w; w.x = pk2(o[0], o[1]); w.y = pk2(o[2], o[3]); w.z = pk2(o[4], o[5]); w.w = pk2(o[6], o[7]);
;                 *(u32x4*)(H + (size_t)row * DFF + col) = w;
.Lp6_tail:
	s_nop 0
	s_nop 0
	v_mov_b32_e32 v33, v24
	v_mov_b32_e32 v24, v29
	v_mov_b32_e32 v29, v26
	v_mov_b32_e32 v26, v31
	v_mov_b32_e32 v31, v16
	v_mov_b32_e32 v16, v21
	v_mov_b32_e32 v21, v18
	v_mov_b32_e32 v18, v23
	v_mov_b32_e32 v32, v28
	v_mov_b32_e32 v28, v30
	v_mov_b32_e32 v30, v20
	v_mov_b32_e32 v20, v22
	v_add_u32_e32 v22, 0xa0, v228
	s_nop 0
	v_fmamk_f32 v23, v241, 0x3a800000, v154
	v_mul_f32_e32 v34, 0x4b800000, v23
	v_cmp_gt_f32_e32 vcc, s45, v23
	s_nop 1
	v_cndmask_b32_e32 v23, v23, v34, vcc
	v_rsq_f32_e32 v34, v23
	v_mad_i64_i32 v[22:23], s[100:101], v22, s46, v[120:121]
	v_lshl_add_u64 v[22:23], v[22:23], 0, v[122:123]
	v_mul_f32_e32 v35, 0x45800000, v34
	v_cndmask_b32_e32 v34, v34, v35, vcc
	v_pk_mul_f32 v[18:19], v[18:19], v[34:35] op_sel_hi:[1,0]
	v_pk_mul_f32 v[32:33], v[32:33], v[34:35] op_sel_hi:[1,0]
	v_pk_mul_f32 v[24:25], v[24:25], v[34:35] op_sel_hi:[1,0]
	v_pk_mul_f32 v[28:29], v[28:29], v[34:35] op_sel_hi:[1,0]
	v_pk_mul_f32 v[26:27], v[26:27], v[34:35] op_sel_hi:[1,0]
	v_pk_mul_f32 v[30:31], v[30:31], v[34:35] op_sel_hi:[1,0]
	v_pk_mul_f32 v[16:17], v[16:17], v[34:35] op_sel_hi:[1,0]
	v_pk_mul_f32 v[20:21], v[20:21], v[34:35] op_sel_hi:[1,0]
	v_mul_f32_e32 v41, 0xbfb8aa3b, v19
	v_mul_f32_e32 v34, 0xbfb8aa3b, v33
	v_mul_f32_e32 v35, 0xbfb8aa3b, v25
	v_mul_f32_e32 v36, 0xbfb8aa3b, v29
	v_mul_f32_e32 v37, 0xbfb8aa3b, v27
	v_mul_f32_e32 v38, 0xbfb8aa3b, v31
	v_mul_f32_e32 v39, 0xbfb8aa3b, v17
	v_mul_f32_e32 v40, 0xbfb8aa3b, v21
	v_exp_f32_e32 v41, v41
	v_exp_f32_e32 v34, v34
	v_exp_f32_e32 v35, v35
	v_exp_f32_e32 v36, v36
	v_exp_f32_e32 v37, v37
	v_exp_f32_e32 v38, v38
	v_exp_f32_e32 v39, v39
	v_exp_f32_e32 v40, v40
	v_add_f32_e32 v41, 1.0, v41
	v_add_f32_e32 v34, 1.0, v34
	v_add_f32_e32 v35, 1.0, v35
	v_add_f32_e32 v36, 1.0, v36
	v_add_f32_e32 v37, 1.0, v37
	v_add_f32_e32 v38, 1.0, v38
	v_add_f32_e32 v39, 1.0, v39
	v_add_f32_e32 v40, 1.0, v40
	v_rcp_f32_e32 v41, v41
	v_rcp_f32_e32 v34, v34
	v_rcp_f32_e32 v35, v35
	v_rcp_f32_e32 v36, v36
	v_rcp_f32_e32 v37, v37
	v_rcp_f32_e32 v38, v38
	v_rcp_f32_e32 v39, v39
	v_rcp_f32_e32 v40, v40
	v_mul_f32_e32 v19, v19, v41
	v_mul_f32_e32 v33, v33, v34
	v_mul_f32_e32 v25, v25, v35
	v_mul_f32_e32 v29, v29, v36
	v_mul_f32_e32 v27, v27, v37
	v_mul_f32_e32 v31, v31, v38
	v_mul_f32_e32 v17, v17, v39
	v_mul_f32_e32 v21, v21, v40
	v_mul_f32_e32 v19, v18, v19
	v_mul_f32_e32 v32, v32, v33
	v_mul_f32_e32 v24, v24, v25
	v_mul_f32_e32 v25, v28, v29
	v_mul_f32_e32 v26, v26, v27
	v_mul_f32_e32 v27, v30, v31
	v_mul_f32_e32 v28, v16, v17
	v_mul_f32_e32 v20, v20, v21
	v_cvt_pk_bf16_f32 v16, v32, v24
	v_cvt_pk_bf16_f32 v17, v25, v26
	v_cvt_pk_bf16_f32 v18, v27, v28
	v_cvt_pk_bf16_f32 v19, v20, v19
	global_store_dwordx4 v[22:23], v[16:19], off
	s_nop 0
	v_mov_b32_e32 v17, v8
	v_mov_b32_e32 v8, v13
	v_mov_b32_e32 v13, v10
	v_mov_b32_e32 v10, v15
	v_mov_b32_e32 v15, v0
	v_mov_b32_e32 v0, v5
	v_mov_b32_e32 v5, v2
	v_mov_b32_e32 v2, v7
	v_mov_b32_e32 v16, v12
	v_mov_b32_e32 v12, v14
	v_mov_b32_e32 v14, v4
	v_mov_b32_e32 v4, v6
	v_add_u32_e32 v6, 0xb0, v228
	s_nop 0
	v_fmamk_f32 v7, v242, 0x3a800000, v154
	v_mul_f32_e32 v18, 0x4b800000, v7
	v_cmp_gt_f32_e64 vcc, s45, v7
	s_nop 1
	v_cndmask_b32_e64 v7, v7, v18, vcc
	v_rsq_f32_e32 v18, v7
	v_mad_i64_i32 v[6:7], s[100:101], v6, s46, v[120:121]
	v_lshl_add_u64 v[6:7], v[6:7], 0, v[122:123]
	v_mul_f32_e32 v19, 0x45800000, v18
	v_cndmask_b32_e64 v18, v18, v19, vcc
	v_pk_mul_f32 v[2:3], v[2:3], v[18:19] op_sel_hi:[1,0]
	v_pk_mul_f32 v[16:17], v[16:17], v[18:19] op_sel_hi:[1,0]
	v_pk_mul_f32 v[8:9], v[8:9], v[18:19] op_sel_hi:[1,0]
	v_pk_mul_f32 v[12:13], v[12:13], v[18:19] op_sel_hi:[1,0]
	v_pk_mul_f32 v[10:11], v[10:11], v[18:19] op_sel_hi:[1,0]
	v_pk_mul_f32 v[14:15], v[14:15], v[18:19] op_sel_hi:[1,0]
	v_pk_mul_f32 v[0:1], v[0:1], v[18:19] op_sel_hi:[1,0]
	v_pk_mul_f32 v[4:5], v[4:5], v[18:19] op_sel_hi:[1,0]
	v_mul_f32_e32 v25, 0xbfb8aa3b, v3
	v_mul_f32_e32 v18, 0xbfb8aa3b, v17
	v_mul_f32_e32 v19, 0xbfb8aa3b, v9
	v_mul_f32_e32 v20, 0xbfb8aa3b, v13
	v_mul_f32_e32 v21, 0xbfb8aa3b, v11
	v_mul_f32_e32 v22, 0xbfb8aa3b, v15
	v_mul_f32_e32 v23, 0xbfb8aa3b, v1
	v_mul_f32_e32 v24, 0xbfb8aa3b, v5
	v_exp_f32_e32 v25, v25
	v_exp_f32_e32 v18, v18
	v_exp_f32_e32 v19, v19
	v_exp_f32_e32 v20, v20
	v_exp_f32_e32 v21, v21
	v_exp_f32_e32 v22, v22
	v_exp_f32_e32 v23, v23
	v_exp_f32_e32 v24, v24
	v_add_f32_e32 v25, 1.0, v25
	v_add_f32_e32 v18, 1.0, v18
	v_add_f32_e32 v19, 1.0, v19
	v_add_f32_e32 v20, 1.0, v20
	v_add_f32_e32 v21, 1.0, v21
	v_add_f32_e32 v22, 1.0, v22
	v_add_f32_e32 v23, 1.0, v23
	v_add_f32_e32 v24, 1.0, v24
	v_rcp_f32_e32 v25, v25
	v_rcp_f32_e32 v18, v18
	v_rcp_f32_e32 v19, v19
	v_rcp_f32_e32 v20, v20
	v_rcp_f32_e32 v21, v21
	v_rcp_f32_e32 v22, v22
	v_rcp_f32_e32 v23, v23
	v_rcp_f32_e32 v24, v24
	v_mul_f32_e32 v3, v3, v25
	v_mul_f32_e32 v17, v17, v18
	v_mul_f32_e32 v9, v9, v19
	v_mul_f32_e32 v13, v13, v20
	v_mul_f32_e32 v11, v11, v21
	v_mul_f32_e32 v15, v15, v22
	v_mul_f32_e32 v1, v1, v23
	v_mul_f32_e32 v5, v5, v24
	v_mul_f32_e32 v3, v2, v3
	v_mul_f32_e32 v16, v16, v17
	v_mul_f32_e32 v8, v8, v9
	v_mul_f32_e32 v9, v12, v13
	v_mul_f32_e32 v10, v10, v11
	v_mul_f32_e32 v11, v14, v15
	v_mul_f32_e32 v12, v0, v1
	v_mul_f32_e32 v4, v4, v5
	v_cvt_pk_bf16_f32 v0, v16, v8
	v_cvt_pk_bf16_f32 v1, v9, v10
	v_cvt_pk_bf16_f32 v2, v11, v12
	v_cvt_pk_bf16_f32 v3, v4, v3
	global_store_dwordx4 v[6:7], v[0:3], off
